# hg_unit: issue all 64 hf/hq ushort loads then one wait (fast path for ch!=0) instead of 32 serialized round trips
# speedup vs baseline: 1.0122x; 1.0122x over previous
; __device__ __forceinline__ void hg_unit(const Ptrs& P, int l, int b, int hd, int ch, unsigned char* lds, int tid) {
;     ...
;         bf16_t hfv[2][16], hqv[2][16];
; #pragma unroll
;         for (int jj = 0; jj < 2; ++jj) { const int j = 2 * sg + jj;
; #pragma unroll
;             for (int t = 0; t < 16; ++t) { hfv[jj][t] = 0; hqv[jj][t] = 0;
;                 if (j < nsub) { const bf16_t* rp = PJ + (row0 + 16 * j + t) * PW + hd * 128 + dk; hfv[jj][t] = rp[C_HF]; hqv[jj][t] = rp[C_HQ]; } } }
.LBB0_525:
	v_and_b32_e32 v33, -2, v107
	v_lshl_add_u64 v[34:35], v[86:87], 0, s[96:97]
	v_lshlrev_b32_e32 v36, 1, v11
	v_mov_b32_e32 v37, v16
	s_and_b64 s[4:5], s[4:5], exec
	v_lshl_add_u64 v[34:35], v[34:35], 0, v[36:37]
	v_lshlrev_b32_e32 v36, 4, v33
	s_cselect_b32 s6, 1, 8
	v_ashrrev_i32_e32 v37, 31, v36
	v_cmp_gt_i32_e64 s[40:41], s6, v33
	v_lshl_add_u64 v[36:37], s[44:45], 0, v[36:37]
	v_bfrev_b32_e32 v39, 1
	v_bfrev_b32_e32 v40, 1
	s_and_b64 vcc, exec, s[76:77]
	s_cbranch_vccz .Lhgf_orig
	s_mov_b64 s[100:101], 0x4200
	v_mad_u64_u32 v[252:253], s[8:9], v36, s34, v[34:35]
	v_mad_i32_i24 v253, v37, s34, v253
	v_add_co_u32_e32 v252, vcc, 0x3000, v252
	s_nop 1
	v_addc_co_u32_e32 v253, vcc, 0, v253, vcc
	global_load_ushort v40, v[252:253], off offset:512
	global_load_ushort v38, v[252:253], off offset:-1536
	v_lshl_add_u64 v[252:253], v[252:253], 0, s[100:101]
	global_load_ushort v39, v[252:253], off offset:512
	global_load_ushort v41, v[252:253], off offset:-1536
	v_lshl_add_u64 v[252:253], v[252:253], 0, s[100:101]
	global_load_ushort v42, v[252:253], off offset:512
	global_load_ushort v43, v[252:253], off offset:-1536
	v_lshl_add_u64 v[252:253], v[252:253], 0, s[100:101]
	global_load_ushort v44, v[252:253], off offset:512
	global_load_ushort v48, v[252:253], off offset:-1536
	v_lshl_add_u64 v[252:253], v[252:253], 0, s[100:101]
	global_load_ushort v50, v[252:253], off offset:512
	global_load_ushort v49, v[252:253], off offset:-1536
	v_lshl_add_u64 v[252:253], v[252:253], 0, s[100:101]
	global_load_ushort v51, v[252:253], off offset:512
	global_load_ushort v55, v[252:253], off offset:-1536
	v_lshl_add_u64 v[252:253], v[252:253], 0, s[100:101]
	global_load_ushort v59, v[252:253], off offset:512
	global_load_ushort v54, v[252:253], off offset:-1536
	v_lshl_add_u64 v[252:253], v[252:253], 0, s[100:101]
	global_load_ushort v58, v[252:253], off offset:512
	global_load_ushort v60, v[252:253], off offset:-1536
	v_lshl_add_u64 v[252:253], v[252:253], 0, s[100:101]
	global_load_ushort v65, v[252:253], off offset:512
	global_load_ushort v56, v[252:253], off offset:-1536
	v_lshl_add_u64 v[252:253], v[252:253], 0, s[100:101]
	global_load_ushort v61, v[252:253], off offset:512
	global_load_ushort v67, v[252:253], off offset:-1536
	v_lshl_add_u64 v[252:253], v[252:253], 0, s[100:101]
	global_load_ushort v79, v[252:253], off offset:512
	global_load_ushort v62, v[252:253], off offset:-1536
	v_lshl_add_u64 v[252:253], v[252:253], 0, s[100:101]
	global_load_ushort v68, v[252:253], off offset:512
	global_load_ushort v75, v[252:253], off offset:-1536
	v_lshl_add_u64 v[252:253], v[252:253], 0, s[100:101]
	global_load_ushort v83, v[252:253], off offset:512
	global_load_ushort v71, v[252:253], off offset:-1536
	v_lshl_add_u64 v[252:253], v[252:253], 0, s[100:101]
	global_load_ushort v77, v[252:253], off offset:512
	global_load_ushort v80, v[252:253], off offset:-1536
	v_lshl_add_u64 v[252:253], v[252:253], 0, s[100:101]
	global_load_ushort v102, v[252:253], off offset:512
	global_load_ushort v73, v[252:253], off offset:-1536
	v_lshl_add_u64 v[252:253], v[252:253], 0, s[100:101]
	global_load_ushort v101, v[252:253], off offset:512
	global_load_ushort v105, v[252:253], off offset:-1536
	v_or_b32_e32 v53, 1, v107
	v_lshlrev_b32_e32 v36, 4, v53
	v_ashrrev_i32_e32 v37, 31, v36
	v_cmp_gt_i32_e64 s[42:43], s6, v53
	v_lshl_add_u64 v[36:37], s[44:45], 0, v[36:37]
	v_mad_u64_u32 v[252:253], s[8:9], v36, s34, v[34:35]
	v_mad_i32_i24 v253, v37, s34, v253
	v_add_co_u32_e32 v252, vcc, 0x3000, v252
	s_nop 1
	v_addc_co_u32_e32 v253, vcc, 0, v253, vcc
	global_load_ushort v66, v[252:253], off offset:512
	global_load_ushort v57, v[252:253], off offset:-1536
	v_lshl_add_u64 v[252:253], v[252:253], 0, s[100:101]
	global_load_ushort v64, v[252:253], off offset:512
	global_load_ushort v69, v[252:253], off offset:-1536
	v_lshl_add_u64 v[252:253], v[252:253], 0, s[100:101]
	global_load_ushort v82, v[252:253], off offset:512
	global_load_ushort v63, v[252:253], off offset:-1536
	v_lshl_add_u64 v[252:253], v[252:253], 0, s[100:101]
	global_load_ushort v70, v[252:253], off offset:512
	global_load_ushort v76, v[252:253], off offset:-1536
	v_lshl_add_u64 v[252:253], v[252:253], 0, s[100:101]
	global_load_ushort v99, v[252:253], off offset:512
	global_load_ushort v72, v[252:253], off offset:-1536
	v_lshl_add_u64 v[252:253], v[252:253], 0, s[100:101]
	global_load_ushort v78, v[252:253], off offset:512
	global_load_ushort v81, v[252:253], off offset:-1536
	v_lshl_add_u64 v[252:253], v[252:253], 0, s[100:101]
	global_load_ushort v104, v[252:253], off offset:512
	global_load_ushort v74, v[252:253], off offset:-1536
	v_lshl_add_u64 v[252:253], v[252:253], 0, s[100:101]
	global_load_ushort v103, v[252:253], off offset:512
	global_load_ushort v109, v[252:253], off offset:-1536
	v_lshl_add_u64 v[252:253], v[252:253], 0, s[100:101]
	global_load_ushort v112, v[252:253], off offset:512
	global_load_ushort v100, v[252:253], off offset:-1536
	v_lshl_add_u64 v[252:253], v[252:253], 0, s[100:101]
	global_load_ushort v110, v[252:253], off offset:512
	global_load_ushort v113, v[252:253], off offset:-1536
	v_lshl_add_u64 v[252:253], v[252:253], 0, s[100:101]
	global_load_ushort v119, v[252:253], off offset:512
	global_load_ushort v111, v[252:253], off offset:-1536
	v_lshl_add_u64 v[252:253], v[252:253], 0, s[100:101]
	global_load_ushort v114, v[252:253], off offset:512
	global_load_ushort v117, v[252:253], off offset:-1536
	v_lshl_add_u64 v[252:253], v[252:253], 0, s[100:101]
	global_load_ushort v121, v[252:253], off offset:512
	global_load_ushort v115, v[252:253], off offset:-1536
	v_lshl_add_u64 v[252:253], v[252:253], 0, s[100:101]
	global_load_ushort v118, v[252:253], off offset:512
	global_load_ushort v120, v[252:253], off offset:-1536
	v_lshl_add_u64 v[252:253], v[252:253], 0, s[100:101]
	global_load_ushort v124, v[252:253], off offset:512
	global_load_ushort v116, v[252:253], off offset:-1536
	v_lshl_add_u64 v[252:253], v[252:253], 0, s[100:101]
	global_load_ushort v122, v[252:253], off offset:512
	global_load_ushort v123, v[252:253], off offset:-1536
	s_waitcnt vmcnt(0)
; __device__ __forceinline__ void hg_unit(const Ptrs& P, int l, int b, int hd, int ch, unsigned char* lds, int tid) {
;     ...
;             for (int t = 0; t < 16; ++t) { hfv[jj][t] = 0; hqv[jj][t] = 0;
;                 if (j < nsub) { const bf16_t* rp = PJ + (row0 + 16 * j + t) * PW + hd * 128 + dk; hfv[jj][t] = rp[C_HF]; hqv[jj][t] = rp[C_HQ]; } } }
; #pragma unroll
;         for (int jj = 0; jj < 2; ++jj) { const int j = 2 * sg + jj;
;             if (j < nsub) {
;                 float kk[16]; float eb = 1.f;
; #pragma unroll
;                 for (int t = 0; t < 16; ++t) {
;                     const float ff = bf2f(hfv[jj][t]); const float qv = bf2f(hqv[jj][t]);
	v_lshlrev_b32_e32 v38, 16, v38
	v_lshlrev_b32_e32 v40, 16, v40
	v_mul_f32_e32 v40, 0xbfb8aa3b, v40
	v_lshlrev_b32_e32 v41, 16, v41
	v_lshlrev_b32_e32 v39, 16, v39
	v_mul_f32_e32 v39, 0xbfb8aa3b, v39
	v_lshlrev_b32_e32 v43, 16, v43
	v_lshlrev_b32_e32 v42, 16, v42
	v_mul_f32_e32 v42, 0xbfb8aa3b, v42
	v_lshlrev_b32_e32 v48, 16, v48
	v_lshlrev_b32_e32 v44, 16, v44
	v_mul_f32_e32 v44, 0xbfb8aa3b, v44
	v_lshlrev_b32_e32 v49, 16, v49
	v_lshlrev_b32_e32 v50, 16, v50
	v_mul_f32_e32 v50, 0xbfb8aa3b, v50
	v_lshlrev_b32_e32 v55, 16, v55
	v_lshlrev_b32_e32 v51, 16, v51
	v_mul_f32_e32 v51, 0xbfb8aa3b, v51
	v_lshlrev_b32_e32 v54, 16, v54
	v_lshlrev_b32_e32 v59, 16, v59
	v_mul_f32_e32 v59, 0xbfb8aa3b, v59
	v_lshlrev_b32_e32 v60, 16, v60
	v_lshlrev_b32_e32 v58, 16, v58
	v_mul_f32_e32 v58, 0xbfb8aa3b, v58
	v_lshlrev_b32_e32 v56, 16, v56
	v_lshlrev_b32_e32 v65, 16, v65
	v_mul_f32_e32 v65, 0xbfb8aa3b, v65
	v_lshlrev_b32_e32 v67, 16, v67
	v_lshlrev_b32_e32 v61, 16, v61
	v_mul_f32_e32 v61, 0xbfb8aa3b, v61
	v_lshlrev_b32_e32 v62, 16, v62
	v_lshlrev_b32_e32 v79, 16, v79
	v_mul_f32_e32 v79, 0xbfb8aa3b, v79
	v_lshlrev_b32_e32 v75, 16, v75
	v_lshlrev_b32_e32 v68, 16, v68
	v_mul_f32_e32 v68, 0xbfb8aa3b, v68
	v_lshlrev_b32_e32 v71, 16, v71
	v_lshlrev_b32_e32 v83, 16, v83
	v_mul_f32_e32 v83, 0xbfb8aa3b, v83
	v_lshlrev_b32_e32 v80, 16, v80
	v_lshlrev_b32_e32 v77, 16, v77
	v_mul_f32_e32 v77, 0xbfb8aa3b, v77
	v_lshlrev_b32_e32 v73, 16, v73
	v_lshlrev_b32_e32 v102, 16, v102
	v_mul_f32_e32 v102, 0xbfb8aa3b, v102
	v_lshlrev_b32_e32 v105, 16, v105
	v_lshlrev_b32_e32 v101, 16, v101
	v_mul_f32_e32 v101, 0xbfb8aa3b, v101
	v_lshlrev_b32_e32 v57, 16, v57
	v_lshlrev_b32_e32 v66, 16, v66
	v_mul_f32_e32 v66, 0xbfb8aa3b, v66
	v_lshlrev_b32_e32 v69, 16, v69
	v_lshlrev_b32_e32 v64, 16, v64
	v_mul_f32_e32 v64, 0xbfb8aa3b, v64
	v_lshlrev_b32_e32 v63, 16, v63
	v_lshlrev_b32_e32 v82, 16, v82
	v_mul_f32_e32 v82, 0xbfb8aa3b, v82
	v_lshlrev_b32_e32 v76, 16, v76
	v_lshlrev_b32_e32 v70, 16, v70
	v_mul_f32_e32 v70, 0xbfb8aa3b, v70
	v_lshlrev_b32_e32 v72, 16, v72
	v_lshlrev_b32_e32 v99, 16, v99
	v_mul_f32_e32 v99, 0xbfb8aa3b, v99
	v_lshlrev_b32_e32 v81, 16, v81
	v_lshlrev_b32_e32 v78, 16, v78
	v_mul_f32_e32 v78, 0xbfb8aa3b, v78
	v_lshlrev_b32_e32 v74, 16, v74
	v_lshlrev_b32_e32 v104, 16, v104
	v_mul_f32_e32 v104, 0xbfb8aa3b, v104
	v_lshlrev_b32_e32 v109, 16, v109
	v_lshlrev_b32_e32 v103, 16, v103
	v_mul_f32_e32 v103, 0xbfb8aa3b, v103
	v_lshlrev_b32_e32 v100, 16, v100
	v_lshlrev_b32_e32 v112, 16, v112
	v_mul_f32_e32 v112, 0xbfb8aa3b, v112
	v_lshlrev_b32_e32 v113, 16, v113
	v_lshlrev_b32_e32 v110, 16, v110
	v_mul_f32_e32 v110, 0xbfb8aa3b, v110
	v_lshlrev_b32_e32 v111, 16, v111
	v_lshlrev_b32_e32 v119, 16, v119
	v_mul_f32_e32 v119, 0xbfb8aa3b, v119
	v_lshlrev_b32_e32 v117, 16, v117
	v_lshlrev_b32_e32 v114, 16, v114
	v_mul_f32_e32 v114, 0xbfb8aa3b, v114
	v_lshlrev_b32_e32 v115, 16, v115
	v_lshlrev_b32_e32 v121, 16, v121
	v_mul_f32_e32 v121, 0xbfb8aa3b, v121
	v_lshlrev_b32_e32 v120, 16, v120
	v_lshlrev_b32_e32 v118, 16, v118
	v_mul_f32_e32 v118, 0xbfb8aa3b, v118
	v_lshlrev_b32_e32 v116, 16, v116
	v_lshlrev_b32_e32 v124, 16, v124
	v_mul_f32_e32 v124, 0xbfb8aa3b, v124
	v_lshlrev_b32_e32 v123, 16, v123
	v_lshlrev_b32_e32 v122, 16, v122
	v_mul_f32_e32 v122, 0xbfb8aa3b, v122
	s_branch .Lhgf_join
.Lhgf_orig:
	s_and_saveexec_b64 s[4:5], s[40:41]
	s_cbranch_execz .LBB0_527
	v_mad_u64_u32 v[40:41], s[8:9], v36, s34, v[34:35]
	v_mad_i32_i24 v38, v37, s34, v41
	v_add_co_u32_e32 v42, vcc, 0x3000, v40
	s_nop 1
	v_addc_co_u32_e32 v43, vcc, 0, v38, vcc
	global_load_ushort v41, v[42:43], off offset:512
	v_add_co_u32_e32 v40, vcc, 0x2000, v40
	s_waitcnt vmcnt(0)
	v_lshlrev_b32_e32 v42, 16, v41
	v_addc_co_u32_e32 v41, vcc, 0, v38, vcc
	global_load_ushort v38, v[40:41], off offset:2560
	v_mul_f32_e32 v40, 0xbfb8aa3b, v42
	s_waitcnt vmcnt(0)
	v_lshlrev_b32_e32 v38, 16, v38

; __device__ __forceinline__ float sigm(float x) { return __builtin_amdgcn_rcpf(1.0f + __expf(-x)); }
; __device__ __forceinline__ unsigned f2bf(float f) { return pk2(f, 0.f) & 0xffffu; }
; __device__ __forceinline__ float sigm(float x) { return __builtin_amdgcn_rcpf(1.0f + __expf(-x)); }
; __device__ __forceinline__ float siluf(float x) { return x * __builtin_amdgcn_rcpf(1.0f + __expf(-x)); }
; __device__ __forceinline__ void hg_unit(const Ptrs& P, int l, int b, int hd, int ch, unsigned char* lds, int tid) {
;     ...
;         for (int jj = 0; jj < 2; ++jj) { const int j = 2 * sg + jj;
;             if (j < nsub) {
;                 float kk[16]; float eb = 1.f;
; #pragma unroll
;                 for (int t = 0; t < 16; ++t) {
;                     const float ff = bf2f(hfv[jj][t]); const float qv = bf2f(hqv[jj][t]);
;                     const float sg1 = sigm(ff); const float f = lb + (1.0f - lb) * sg1; eb *= f;
;                     const float kv = (1.0f - lb) * (1.0f - sg1);
;                     const float ebi = __builtin_amdgcn_rcpf(eb);
;                     kk[t] = kv * ebi;
;                     Qb[(16 * j + t) * 136 + dk] = (bf16_t)f2bf(siluf(qv) * eb);
;                     Kb[(16 * j + t) * 136 + dk] = (bf16_t)f2bf(kk[t]); }
.Lhgf_join:
	s_add_i32 s3, 0, 0x1b000
	v_lshl_add_u32 v35, v11, 2, s3
	v_sub_f32_e32 v34, 1.0, v32
	s_and_saveexec_b64 s[4:5], s[40:41]
	s_cbranch_execz .LBB0_591
	v_mul_f32_e32 v36, 0xbfb8aa3b, v38
	v_exp_f32_e32 v36, v36
	v_exp_f32_e32 v37, v40
	v_exp_f32_e32 v39, v39
	v_exp_f32_e32 v42, v42
	v_add_f32_e32 v36, 1.0, v36
	v_rcp_f32_e32 v45, v36
	v_add_f32_e32 v36, 1.0, v37
	v_add_f32_e32 v37, 1.0, v39
	v_rcp_f32_e32 v36, v36
	v_mul_f32_e32 v45, v38, v45
	v_mul_f32_e32 v38, 0xbfb8aa3b, v41
	v_exp_f32_e32 v39, v38
	v_rcp_f32_e32 v37, v37
	s_movk_i32 s7, 0x880
	v_mul_lo_u32 v40, v33, s7
	v_add_f32_e32 v39, 1.0, v39
	v_rcp_f32_e32 v39, v39
	v_or_b32_e32 v40, v40, v11
	v_pk_fma_f32 v[126:127], v[34:35], v[36:37], v[32:33] op_sel_hi:[0,1,0]
	v_lshl_add_u32 v125, v40, 1, 0
	v_mul_f32_e32 v40, v126, v45
	v_mul_f32_e32 v45, v41, v39
	v_add_f32_e32 v39, 1.0, v42
	v_rcp_f32_e32 v41, v39
	v_cvt_pk_bf16_f32 v40, v40, s0
	ds_write_b16 v125, v40
	v_mov_b32_e32 v128, v126
	v_mov_b32_e32 v129, v34
	v_mov_b32_e32 v40, v127
	v_mul_f32_e32 v39, 0xbfb8aa3b, v43
	v_rcp_f32_e32 v38, v126
	v_pk_mul_f32 v[126:127], v[128:129], v[40:41]
	v_exp_f32_e32 v40, v39
	v_mul_f32_e32 v42, v45, v126
	v_cvt_pk_bf16_f32 v142, v42, s0
	v_add_f32_e32 v42, v32, v127
	v_add_f32_e32 v40, 1.0, v40
	v_rcp_f32_e32 v40, v40
	v_rcp_f32_e32 v39, v126
	v_mul_f32_e32 v126, v126, v42
	v_rcp_f32_e32 v42, v126
	v_mul_f32_e32 v40, v43, v40
	v_exp_f32_e32 v43, v44
	v_mul_f32_e32 v44, 0xbfb8aa3b, v48
	v_exp_f32_e32 v44, v44
	v_mul_f32_e32 v40, v40, v126
	v_cvt_pk_bf16_f32 v143, v40, s0
	v_add_f32_e32 v43, 1.0, v43
	v_add_f32_e32 v40, 1.0, v44
	v_rcp_f32_e32 v40, v40
	v_rcp_f32_e32 v45, v43
	v_pk_add_f32 v[36:37], v[36:37], 1.0 op_sel_hi:[1,0] neg_lo:[1,0] neg_hi:[1,0]
	v_mul_f32_e32 v40, v48, v40
	v_exp_f32_e32 v48, v50
	v_mul_f32_e32 v50, 0xbfb8aa3b, v49
	v_exp_f32_e32 v50, v50
	v_fma_f32 v43, v34, v45, v32
	v_mul_f32_e32 v44, v126, v43
	v_mul_f32_e32 v40, v40, v44
	v_cvt_pk_bf16_f32 v144, v40, s0
	v_add_f32_e32 v40, 1.0, v50
	v_rcp_f32_e32 v40, v40
	v_add_f32_e32 v48, 1.0, v48
	v_rcp_f32_e32 v48, v48
	v_rcp_f32_e32 v43, v44
	v_mul_f32_e32 v40, v49, v40
	v_exp_f32_e32 v49, v51
	v_mul_f32_e32 v51, 0xbfb8aa3b, v55
	v_exp_f32_e32 v51, v51
	v_fma_f32 v50, v34, v48, v32
	v_mul_f32_e32 v44, v44, v50
	v_mul_f32_e32 v40, v40, v44
	v_cvt_pk_bf16_f32 v145, v40, s0
	v_add_f32_e32 v40, 1.0, v51
	v_rcp_f32_e32 v40, v40
	v_add_f32_e32 v49, 1.0, v49
	v_rcp_f32_e32 v49, v49
	v_rcp_f32_e32 v50, v44
	v_mul_f32_e32 v40, v55, v40
	v_exp_f32_e32 v55, v59
	v_mul_f32_e32 v59, 0xbfb8aa3b, v54
	v_exp_f32_e32 v59, v59
	v_fma_f32 v51, v34, v49, v32
	v_mul_f32_e32 v44, v44, v51
	v_mul_f32_e32 v40, v40, v44
	v_cvt_pk_bf16_f32 v146, v40, s0
	v_add_f32_e32 v40, 1.0, v59
	v_rcp_f32_e32 v40, v40
	v_add_f32_e32 v55, 1.0, v55
	v_rcp_f32_e32 v126, v55
	v_rcp_f32_e32 v51, v44
	v_mul_f32_e32 v40, v54, v40
	v_exp_f32_e32 v54, v58
	v_fma_f32 v55, v34, v126, v32
	v_mul_f32_e32 v44, v44, v55
	v_mul_f32_e32 v55, 0xbfb8aa3b, v60
	v_add_f32_e32 v54, 1.0, v54
	v_rcp_f32_e32 v127, v54
	v_exp_f32_e32 v55, v55
	v_rcp_f32_e32 v128, v44
	v_mul_f32_e32 v40, v40, v44
	v_fma_f32 v54, v34, v127, v32
	v_mul_f32_e32 v44, v44, v54
	v_exp_f32_e32 v54, v65
	v_cvt_pk_bf16_f32 v147, v40, s0
	v_add_f32_e32 v40, 1.0, v55
	v_rcp_f32_e32 v40, v40
	v_mul_f32_e32 v55, 0xbfb8aa3b, v56
	v_add_f32_e32 v54, 1.0, v54
	v_exp_f32_e32 v55, v55
	v_rcp_f32_e32 v54, v54
	v_mul_f32_e32 v40, v60, v40
	v_mul_f32_e32 v40, v40, v44
	v_cvt_pk_bf16_f32 v65, v40, s0
	v_add_f32_e32 v40, 1.0, v55
	v_fma_f32 v55, v34, v54, v32
	v_rcp_f32_e32 v129, v44
	v_rcp_f32_e32 v40, v40
	v_mul_f32_e32 v44, v44, v55
	v_exp_f32_e32 v55, v61
	v_rcp_f32_e32 v58, v44
	v_mul_f32_e32 v40, v56, v40
	v_mul_f32_e32 v56, 0xbfb8aa3b, v67
	v_add_f32_e32 v55, 1.0, v55
	v_exp_f32_e32 v56, v56
	v_rcp_f32_e32 v55, v55
	v_mul_f32_e32 v40, v40, v44
	v_cvt_pk_bf16_f32 v148, v40, s0
	v_add_f32_e32 v40, 1.0, v56
	v_fma_f32 v56, v34, v55, v32
	v_mul_f32_e32 v44, v44, v56
	v_exp_f32_e32 v56, v79
	v_rcp_f32_e32 v40, v40
	v_mul_f32_e32 v60, 0xbfb8aa3b, v62
	v_exp_f32_e32 v61, v60
	v_add_f32_e32 v56, 1.0, v56
	v_rcp_f32_e32 v60, v56
	v_mul_f32_e32 v40, v67, v40
	v_mul_f32_e32 v40, v40, v44
	v_cvt_pk_bf16_f32 v56, v40, s0
	v_add_f32_e32 v40, 1.0, v61
	v_fma_f32 v61, v34, v60, v32
	v_rcp_f32_e32 v59, v44
	v_rcp_f32_e32 v40, v40
	v_mul_f32_e32 v44, v44, v61
	v_exp_f32_e32 v61, v68
	v_rcp_f32_e32 v130, v44
	v_mul_f32_e32 v40, v62, v40
	v_mul_f32_e32 v62, 0xbfb8aa3b, v75
	v_add_f32_e32 v61, 1.0, v61
	v_exp_f32_e32 v62, v62
	v_rcp_f32_e32 v61, v61
	v_mul_f32_e32 v40, v40, v44
	v_cvt_pk_bf16_f32 v67, v40, s0
	v_add_f32_e32 v40, 1.0, v62
	v_fma_f32 v62, v34, v61, v32
	v_mul_f32_e32 v44, v44, v62
	v_exp_f32_e32 v62, v83
	v_rcp_f32_e32 v40, v40
	v_mul_f32_e32 v68, 0xbfb8aa3b, v71
	v_exp_f32_e32 v68, v68
	v_add_f32_e32 v62, 1.0, v62
	v_rcp_f32_e32 v132, v62
	v_mul_f32_e32 v40, v75, v40
	v_mul_f32_e32 v40, v40, v44
	v_cvt_pk_bf16_f32 v62, v40, s0
	v_add_f32_e32 v40, 1.0, v68
	v_rcp_f32_e32 v40, v40
	v_fma_f32 v68, v34, v132, v32
	v_rcp_f32_e32 v131, v44
	v_mul_f32_e32 v44, v44, v68
	v_exp_f32_e32 v68, v77
	v_mul_f32_e32 v40, v71, v40
	v_mul_f32_e32 v71, 0xbfb8aa3b, v80
	v_exp_f32_e32 v71, v71
; __device__ __forceinline__ float sigm(float x) { return __builtin_amdgcn_rcpf(1.0f + __expf(-x)); }
; __device__ __forceinline__ unsigned pk2(float lo, float hi) { f32x2_t v = {lo, hi}; bf16x2_t b = __builtin_convertvector(v, bf16x2_t); return __builtin_bit_cast(unsigned, b); }
; __device__ __forceinline__ unsigned f2bf(float f) { return pk2(f, 0.f) & 0xffffu; }
; __device__ __forceinline__ float sigm(float x) { return __builtin_amdgcn_rcpf(1.0f + __expf(-x)); }
; __device__ __forceinline__ float siluf(float x) { return x * __builtin_amdgcn_rcpf(1.0f + __expf(-x)); }
; __device__ __forceinline__ void hg_unit(const Ptrs& P, int l, int b, int hd, int ch, unsigned char* lds, int tid) {
;     ...
;                 for (int t = 0; t < 16; ++t) {
;                     const float ff = bf2f(hfv[jj][t]); const float qv = bf2f(hqv[jj][t]);
;                     const float sg1 = sigm(ff); const float f = lb + (1.0f - lb) * sg1; eb *= f;
;                     const float kv = (1.0f - lb) * (1.0f - sg1);
;                     const float ebi = __builtin_amdgcn_rcpf(eb);
;                     kk[t] = kv * ebi;
;                     Qb[(16 * j + t) * 136 + dk] = (bf16_t)f2bf(siluf(qv) * eb);
;                     Kb[(16 * j + t) * 136 + dk] = (bf16_t)f2bf(kk[t]); }
;                 const float ebe = eb;
; #pragma unroll
;                 for (int t = 0; t < 16; t += 2) *(unsigned*)(Ket + (j * 128 + dk) * 20 + t) = pk2(kk[t] * ebe, kk[t + 1] * ebe);
;                 EBE[j * 128 + dk] = ebe;
	v_add_f32_e32 v68, 1.0, v68
	v_rcp_f32_e32 v133, v68
	v_mul_f32_e32 v40, v40, v44
	v_cvt_pk_bf16_f32 v68, v40, s0
	v_add_f32_e32 v40, 1.0, v71
	v_rcp_f32_e32 v40, v40
	v_fma_f32 v71, v34, v133, v32
	v_rcp_f32_e32 v134, v44
	v_mul_f32_e32 v44, v44, v71
	v_exp_f32_e32 v71, v102
	v_mul_f32_e32 v75, 0xbfb8aa3b, v73
	v_exp_f32_e32 v75, v75
	v_mul_f32_e32 v40, v80, v40
	v_mul_f32_e32 v40, v40, v44
	v_add_f32_e32 v71, 1.0, v71
	v_rcp_f32_e32 v136, v71
	v_cvt_pk_bf16_f32 v71, v40, s0
	v_add_f32_e32 v40, 1.0, v75
	v_rcp_f32_e32 v40, v40
	v_fma_f32 v75, v34, v136, v32
	v_rcp_f32_e32 v135, v44
	v_mul_f32_e32 v44, v44, v75
	v_mul_f32_e32 v40, v73, v40
	v_exp_f32_e32 v73, v101
	v_mul_f32_e32 v75, 0xbfb8aa3b, v105
	v_exp_f32_e32 v75, v75
	v_mul_f32_e32 v40, v40, v44
	v_add_f32_e32 v73, 1.0, v73
	v_rcp_f32_e32 v137, v73
	v_cvt_pk_bf16_f32 v73, v40, s0
	v_add_f32_e32 v40, 1.0, v75
	v_rcp_f32_e32 v75, v40
	v_fma_f32 v40, v34, v137, v32
	v_rcp_f32_e32 v138, v44
	v_mul_f32_e32 v40, v44, v40
	v_mul_f32_e32 v44, v105, v75
	v_pk_mul_f32 v[36:37], v[34:35], v[36:37] op_sel_hi:[0,1]
	v_mul_f32_e32 v44, v44, v40
	v_pk_mul_f32 v[36:37], v[36:37], v[38:39]
	v_cvt_pk_bf16_f32 v75, v44, s0
	v_lshl_or_b32 v44, v33, 7, v11
	v_cvt_pk_bf16_f32 v38, v36, s0
	v_mad_u64_u32 v[140:141], s[8:9], v44, 40, v[16:17]
	ds_write_b16 v125, v38 offset:34816
	ds_write_b16 v125, v142 offset:272
	v_cvt_pk_bf16_f32 v38, v37, s0
	v_mov_b32_e32 v44, v41
	ds_write_b16 v125, v38 offset:35088
	ds_write_b16 v125, v143 offset:544
	v_pk_add_f32 v[38:39], v[44:45], 1.0 op_sel_hi:[1,0] neg_lo:[1,0] neg_hi:[1,0]
	v_pk_mul_f32 v[36:37], v[36:37], v[40:41] op_sel_hi:[1,0]
	v_pk_mul_f32 v[38:39], v[34:35], v[38:39] op_sel_hi:[0,1]
	v_pk_mul_f32 v[38:39], v[38:39], v[42:43]
	v_cvt_pk_bf16_f32 v36, v36, v37
	v_cvt_pk_bf16_f32 v41, v39, s0
	v_cvt_pk_bf16_f32 v37, v38, s0
	v_pk_mul_f32 v[38:39], v[38:39], v[40:41] op_sel_hi:[1,0]
	ds_write_b16 v125, v37 offset:35360
	ds_write_b16 v125, v144 offset:816
	ds_write_b16 v125, v41 offset:35632
	ds_write_b16 v125, v145 offset:1088
	v_cvt_pk_bf16_f32 v37, v38, v39
	v_pk_add_f32 v[38:39], v[48:49], 1.0 op_sel_hi:[1,0] neg_lo:[1,0] neg_hi:[1,0]
	v_add_u32_e32 v77, 0x11000, v140
	v_pk_mul_f32 v[38:39], v[34:35], v[38:39] op_sel_hi:[0,1]
	v_pk_mul_f32 v[38:39], v[38:39], v[50:51]
	v_rcp_f32_e32 v139, v40
	v_cvt_pk_bf16_f32 v41, v38, s0
	v_cvt_pk_bf16_f32 v42, v39, s0
	ds_write_b16 v125, v41 offset:35904
	ds_write_b16 v125, v146 offset:1360
	ds_write_b16 v125, v42 offset:36176
	ds_write_b16 v125, v147 offset:1632
	v_pk_add_f32 v[42:43], v[126:127], 1.0 op_sel_hi:[1,0] neg_lo:[1,0] neg_hi:[1,0]
	v_pk_mul_f32 v[38:39], v[38:39], v[40:41] op_sel_hi:[1,0]
	v_pk_mul_f32 v[42:43], v[34:35], v[42:43] op_sel_hi:[0,1]
	v_pk_mul_f32 v[42:43], v[42:43], v[128:129]
	v_cvt_pk_bf16_f32 v38, v38, v39
	v_cvt_pk_bf16_f32 v41, v43, s0
	v_cvt_pk_bf16_f32 v39, v42, s0
	v_pk_mul_f32 v[42:43], v[42:43], v[40:41] op_sel_hi:[1,0]
	ds_write_b16 v125, v39 offset:36448
	ds_write_b16 v125, v65 offset:1904
	ds_write_b16 v125, v41 offset:36720
	ds_write_b16 v125, v148 offset:2176
	v_cvt_pk_bf16_f32 v39, v42, v43
	ds_write2_b64 v77, v[36:37], v[38:39] offset1:1
	v_pk_add_f32 v[36:37], v[54:55], 1.0 op_sel_hi:[1,0] neg_lo:[1,0] neg_hi:[1,0]
	v_lshl_add_u32 v33, v33, 9, v35
	v_pk_mul_f32 v[36:37], v[34:35], v[36:37] op_sel_hi:[0,1]
	v_pk_mul_f32 v[36:37], v[36:37], v[58:59]
	s_nop 0
	v_cvt_pk_bf16_f32 v38, v36, s0
	v_cvt_pk_bf16_f32 v39, v37, s0
	ds_write_b16 v125, v38 offset:36992
	ds_write_b16 v125, v56 offset:2448
	ds_write_b16 v125, v39 offset:37264
	ds_write_b16 v125, v67 offset:2720
	v_pk_add_f32 v[38:39], v[60:61], 1.0 op_sel_hi:[1,0] neg_lo:[1,0] neg_hi:[1,0]
	v_pk_mul_f32 v[36:37], v[36:37], v[40:41] op_sel_hi:[1,0]
	v_pk_mul_f32 v[38:39], v[34:35], v[38:39] op_sel_hi:[0,1]
	v_pk_mul_f32 v[38:39], v[38:39], v[130:131]
	v_cvt_pk_bf16_f32 v36, v36, v37
	v_cvt_pk_bf16_f32 v41, v39, s0
	v_cvt_pk_bf16_f32 v37, v38, s0
	v_pk_mul_f32 v[38:39], v[38:39], v[40:41] op_sel_hi:[1,0]
	ds_write_b16 v125, v37 offset:37536
	ds_write_b16 v125, v62 offset:2992
	ds_write_b16 v125, v41 offset:37808
	ds_write_b16 v125, v68 offset:3264
	v_cvt_pk_bf16_f32 v37, v38, v39
	v_pk_add_f32 v[38:39], v[132:133], 1.0 op_sel_hi:[1,0] neg_lo:[1,0] neg_hi:[1,0]
	s_nop 0
	v_pk_mul_f32 v[38:39], v[34:35], v[38:39] op_sel_hi:[0,1]
	v_pk_mul_f32 v[38:39], v[38:39], v[134:135]
	s_nop 0
	v_cvt_pk_bf16_f32 v41, v38, s0
	v_cvt_pk_bf16_f32 v42, v39, s0
	ds_write_b16 v125, v41 offset:38080
	ds_write_b16 v125, v71 offset:3536
	ds_write_b16 v125, v42 offset:38352
	ds_write_b16 v125, v73 offset:3808
	v_pk_add_f32 v[42:43], v[136:137], 1.0 op_sel_hi:[1,0] neg_lo:[1,0] neg_hi:[1,0]
	v_pk_mul_f32 v[38:39], v[38:39], v[40:41] op_sel_hi:[1,0]
	v_pk_mul_f32 v[42:43], v[34:35], v[42:43] op_sel_hi:[0,1]
	v_pk_mul_f32 v[42:43], v[42:43], v[138:139]
	v_cvt_pk_bf16_f32 v38, v38, v39
	v_cvt_pk_bf16_f32 v41, v43, s0
	v_cvt_pk_bf16_f32 v39, v42, s0
	v_pk_mul_f32 v[42:43], v[40:41], v[42:43] op_sel_hi:[0,1]
	ds_write_b16 v125, v39 offset:38624
	ds_write_b16 v125, v75 offset:4080
	ds_write_b16 v125, v41 offset:38896
	v_cvt_pk_bf16_f32 v39, v42, v43
	ds_write2_b64 v77, v[36:37], v[38:39] offset0:2 offset1:3
	ds_write_b32 v33, v40

; __global__ void __launch_bounds__(512, 2) fwd_megakernel(Ptrs Parg) {
	.amdhsa_kernel _Z14fwd_megakernel4Ptrs
		.amdhsa_group_segment_fixed_size 0
		.amdhsa_private_segment_fixed_size 0
		.amdhsa_kernarg_size 448
		.amdhsa_user_sgpr_count 2
		.amdhsa_user_sgpr_dispatch_ptr 0
		.amdhsa_user_sgpr_queue_ptr 0
		.amdhsa_user_sgpr_kernarg_segment_ptr 1
		.amdhsa_user_sgpr_dispatch_id 0
		.amdhsa_user_sgpr_kernarg_preload_length 0
		.amdhsa_user_sgpr_kernarg_preload_offset 0
		.amdhsa_user_sgpr_private_segment_size 0
		.amdhsa_uses_dynamic_stack 0
		.amdhsa_enable_private_segment 0
		.amdhsa_system_sgpr_workgroup_id_x 1
		.amdhsa_system_sgpr_workgroup_id_y 0
		.amdhsa_system_sgpr_workgroup_id_z 0
		.amdhsa_system_sgpr_workgroup_info 0
		.amdhsa_system_vgpr_workitem_id 2
		.amdhsa_next_free_vgpr 256
		.amdhsa_next_free_sgpr 102
		.amdhsa_accum_offset 256
		.amdhsa_reserve_vcc 1
		.amdhsa_float_round_mode_32 0
		.amdhsa_float_round_mode_16_64 0
		.amdhsa_float_denorm_mode_32 3
		.amdhsa_float_denorm_mode_16_64 3
		.amdhsa_dx10_clamp 1
		.amdhsa_ieee_mode 1
		.amdhsa_fp16_overflow 0
		.amdhsa_tg_split 0
		.amdhsa_exception_fp_ieee_invalid_op 0
		.amdhsa_exception_fp_denorm_src 0
		.amdhsa_exception_fp_ieee_div_zero 0
		.amdhsa_exception_fp_ieee_overflow 0
		.amdhsa_exception_fp_ieee_underflow 0
		.amdhsa_exception_fp_ieee_inexact 0
		.amdhsa_exception_int_div_zero 0
	.end_amdhsa_kernel

; __global__ void __launch_bounds__(512, 2) fwd_megakernel(Ptrs Parg) {
amdhsa.kernels:
  - .agpr_count:     0
    .args:
      - .offset:         0
        .size:           192
        .value_kind:     by_value
      - .offset:         192
        .size:           4
        .value_kind:     hidden_block_count_x
      - .offset:         196
        .size:           4
        .value_kind:     hidden_block_count_y
      - .offset:         200
        .size:           4
        .value_kind:     hidden_block_count_z
      - .offset:         204
        .size:           2
        .value_kind:     hidden_group_size_x
      - .offset:         206
        .size:           2
        .value_kind:     hidden_group_size_y
      - .offset:         208
        .size:           2
        .value_kind:     hidden_group_size_z
      - .offset:         210
        .size:           2
        .value_kind:     hidden_remainder_x
      - .offset:         212
        .size:           2
        .value_kind:     hidden_remainder_y
      - .offset:         214
        .size:           2
        .value_kind:     hidden_remainder_z
      - .offset:         232
        .size:           8
        .value_kind:     hidden_global_offset_x
      - .offset:         240
        .size:           8
        .value_kind:     hidden_global_offset_y
      - .offset:         248
        .size:           8
        .value_kind:     hidden_global_offset_z
      - .offset:         256
        .size:           2
        .value_kind:     hidden_grid_dims
      - .offset:         280
        .size:           8
        .value_kind:     hidden_multigrid_sync_arg
      - .offset:         312
        .size:           4
        .value_kind:     hidden_dynamic_lds_size
    .group_segment_fixed_size: 0
    .kernarg_segment_align: 8
    .kernarg_segment_size: 448
    .language:       OpenCL C
    .language_version:
      - 2
      - 0
    .max_flat_workgroup_size: 512
    .name:           _Z14fwd_megakernel4Ptrs
    .private_segment_fixed_size: 0
    .sgpr_count:     108
    .sgpr_spill_count: 106
    .symbol:         _Z14fwd_megakernel4Ptrs.kd
    .uniform_work_group_size: 1
    .uses_dynamic_stack: false
    .vgpr_count:     256
    .vgpr_spill_count: 0
    .wavefront_size: 64
